# differential loop role A: staging stores after the first half of its PV MFMAs (role B still in its softmax), no LDS-write tail left in either role
# baseline (speedup 1.0000x reference)
; template <bool DIFF>
; __device__ __forceinline__ void attn_unit(const AttnP& A, int b, int h, int qi, ldsp lds) {
;     ...
;             QK_BLOCK();
;             s16x4 vlo[8], vhi[8];
; #pragma unroll
;             for (int t = 0; t < 2; ++t)
; #pragma unroll
;                 for (int j = 0; j < 4; ++j) { vlo[t * 4 + j] = vtr(Vb + trb + (16 * j) * VP + t * 64); vhi[t * 4 + j] = vtr(Vb + trb + (16 * j + 8) * VP + t * 64); }
;             __builtin_amdgcn_sched_barrier(0);
;             MASK_BLOCK();
;             bool full = (kt == kt0);
;             float psa, psb;
;             if (!full) {
;                 EXPSUM_BLOCK();
;                 if (__any(psa + psb > 1.0e18f)) { full = true; QK_BLOCK();
;     ...
;             bf16x8 pw[4];
; #pragma unroll
;             for (int j = 0; j < 4; ++j) {
;                 u32x4 pk;
;                 if (j < 2) { const int rb = 8 * (j & 1); pk.x = cvtpk(s0[rb], s0[rb + 1]); pk.y = cvtpk(s0[rb + 2], s0[rb + 3]); pk.z = cvtpk(s0[rb + 4], s0[rb + 5]); pk.w = cvtpk(s0[rb + 6], s0[rb + 7]); }
;                 else { const int rb = 8 * (j & 1); pk.x = cvtpk(s1[rb], s1[rb + 1]); pk.y = cvtpk(s1[rb + 2], s1[rb + 3]); pk.z = cvtpk(s1[rb + 4], s1[rb + 5]); pk.w = cvtpk(s1[rb + 6], s1[rb + 7]); }
;                 pw[j] = __builtin_bit_cast(bf16x8, pk);
;             }
;             __builtin_amdgcn_sched_barrier(0);
;             __builtin_amdgcn_s_setprio(1);
; #pragma unroll
;             for (int t = 0; t < 2; ++t)
; #pragma unroll
;                 for (int j = 0; j < 4; ++j) {
;                     const bf16x8 vf = (bf16x8){vlo[t * 4 + j][0], vlo[t * 4 + j][1], vlo[t * 4 + j][2], vlo[t * 4 + j][3], vhi[t * 4 + j][0], vhi[t * 4 + j][1], vhi[t * 4 + j][2], vhi[t * 4 + j][3]};
;                     o[t] = __builtin_amdgcn_mfma_f32_32x32x16_bf16(vf, pw[j], o[t], 0, 0, 0);
;                 }
;             if (DIFF) {
; #pragma unroll
;                 for (int t = 2; t < NTD; ++t)
; #pragma unroll
;                     for (int j = 0; j < 4; ++j) { vlo[(t - 2) * 4 + j] = vtr(Vb + trb + (16 * j) * VP + t * 64); vhi[(t - 2) * 4 + j] = vtr(Vb + trb + (16 * j + 8) * VP + t * 64); }
;                 __builtin_amdgcn_sched_barrier(0);
; #pragma unroll
;                 for (int t = 2; t < NTD; ++t)
; #pragma unroll
;                     for (int j = 0; j < 4; ++j) {
;                         const int i = (t - 2) * 4 + j;
.Lda_s_even:
	ds_read_b64_tr_b16 v[148:149], v252 offset:17472
	ds_read_b64_tr_b16 v[150:151], v252 offset:20032
	ds_read_b64_tr_b16 v[152:153], v252 offset:17408
	ds_read_b64_tr_b16 v[154:155], v252 offset:19968
	ds_read_b64_tr_b16 v[156:157], v252 offset:22592
	ds_read_b64_tr_b16 v[158:159], v252 offset:25152
	ds_read_b64_tr_b16 v[160:161], v252 offset:22528
	ds_read_b64_tr_b16 v[162:163], v252 offset:25088
	ds_read_b64_tr_b16 v[164:165], v252 offset:27712
	ds_read_b64_tr_b16 v[166:167], v252 offset:30272
	ds_read_b64_tr_b16 v[168:169], v252 offset:27648
	ds_read_b64_tr_b16 v[170:171], v252 offset:30208
	ds_read_b64_tr_b16 v[172:173], v252 offset:32768
	ds_read_b64_tr_b16 v[174:175], v252 offset:35328
	ds_read_b64_tr_b16 v[176:177], v252 offset:32832
	ds_read_b64_tr_b16 v[178:179], v252 offset:35392
	s_waitcnt lgkmcnt(14)
	v_mfma_f32_32x32x16_bf16 v[34:49], v[148:151], v[98:101], v[34:49]
	ds_read_b64_tr_b16 v[90:91], v252 offset:17536
	ds_read_b64_tr_b16 v[92:93], v252 offset:20096
	s_waitcnt lgkmcnt(14)
	v_mfma_f32_32x32x16_bf16 v[50:65], v[152:155], v[98:101], v[50:65]
	ds_read_b64_tr_b16 v[94:95], v252 offset:17600
	ds_read_b64_tr_b16 v[96:97], v252 offset:20160
	s_waitcnt lgkmcnt(14)
	v_mfma_f32_32x32x16_bf16 v[34:49], v[156:159], v[102:105], v[34:49]
	ds_read_b64_tr_b16 v[106:107], v252 offset:22656
	ds_read_b64_tr_b16 v[108:109], v252 offset:25216
	s_waitcnt lgkmcnt(14)
	v_mfma_f32_32x32x16_bf16 v[50:65], v[160:163], v[102:105], v[50:65]
	ds_read_b64_tr_b16 v[110:111], v252 offset:22720
	ds_read_b64_tr_b16 v[112:113], v252 offset:25280
	s_waitcnt lgkmcnt(14)
	v_mfma_f32_32x32x16_bf16 v[34:49], v[164:167], v[82:85], v[34:49]
	ds_read_b64_tr_b16 v[240:241], v252 offset:27776
	ds_read_b64_tr_b16 v[242:243], v252 offset:30336
	s_waitcnt lgkmcnt(14)
	v_mfma_f32_32x32x16_bf16 v[50:65], v[168:171], v[82:85], v[50:65]
	ds_read_b64_tr_b16 v[148:149], v252 offset:27840
	ds_read_b64_tr_b16 v[150:151], v252 offset:30400
	s_waitcnt lgkmcnt(14)
	v_mfma_f32_32x32x16_bf16 v[50:65], v[172:175], v[86:89], v[50:65]
	ds_read_b64_tr_b16 v[152:153], v252 offset:32896
	ds_read_b64_tr_b16 v[154:155], v252 offset:35456
	s_waitcnt lgkmcnt(14)
	v_mfma_f32_32x32x16_bf16 v[34:49], v[176:179], v[86:89], v[34:49]
	ds_read_b64_tr_b16 v[156:157], v252 offset:32960
	ds_read_b64_tr_b16 v[158:159], v252 offset:35520
	s_waitcnt vmcnt(0)
	ds_write_b128 v226, v[132:135] offset:38144
	ds_write_b128 v228, v[140:143] offset:38144
	ds_write_b128 v227, v[136:139] offset:17408
	ds_write_b128 v229, v[144:147] offset:17408
	global_load_dwordx4 v[136:139], v[196:197], off offset:2048
	global_load_dwordx4 v[144:147], v[198:199], off offset:2048
	v_lshl_add_u64 v[196:197], v[196:197], 0, s[26:27]
	v_lshl_add_u64 v[198:199], v[198:199], 0, s[26:27]
	global_load_dwordx4 v[132:135], v[196:197], off offset:1024
	global_load_dwordx4 v[140:143], v[198:199], off offset:1024
	s_waitcnt lgkmcnt(15)
	v_mfma_f32_32x32x16_bf16 v[18:33], v[90:93], v[98:101], v[18:33]
	ds_read_b128 v[160:163], v234
	s_waitcnt lgkmcnt(15)
	v_mfma_f32_32x32x16_bf16 v[2:17], v[94:97], v[98:101], v[2:17]
	ds_read_b128 v[164:167], v234 offset:8704
	s_waitcnt lgkmcnt(15)
	v_mfma_f32_32x32x16_bf16 v[18:33], v[106:109], v[102:105], v[18:33]
	ds_read_b128 v[168:171], v234 offset:32
	s_waitcnt lgkmcnt(15)
	v_mfma_f32_32x32x16_bf16 v[2:17], v[110:113], v[102:105], v[2:17]
	ds_read_b128 v[172:175], v234 offset:8736
	s_waitcnt lgkmcnt(14)
	v_mfma_f32_32x32x16_bf16 v[18:33], v[240:243], v[82:85], v[18:33]
	ds_read_b128 v[176:179], v234 offset:64
	s_waitcnt lgkmcnt(13)
	v_mfma_f32_32x32x16_bf16 v[2:17], v[148:151], v[82:85], v[2:17]
	ds_read_b128 v[240:243], v234 offset:8768
	s_waitcnt lgkmcnt(12)
	v_mfma_f32_32x32x16_bf16 v[18:33], v[152:155], v[86:89], v[18:33]
	ds_read_b128 v[148:151], v234 offset:96
	s_waitcnt lgkmcnt(11)
	v_mfma_f32_32x32x16_bf16 v[2:17], v[156:159], v[86:89], v[2:17]
	ds_read_b128 v[152:155], v234 offset:8800
	s_waitcnt lgkmcnt(7)
	v_mfma_f32_32x32x16_bf16 v[98:113], v[160:163], v[116:119], v[66:81]
	s_waitcnt lgkmcnt(6)
	v_mfma_f32_32x32x16_bf16 v[82:97], v[164:167], v[116:119], v[66:81]
	s_waitcnt lgkmcnt(5)
	v_mfma_f32_32x32x16_bf16 v[98:113], v[168:171], v[120:123], v[98:113]
	s_waitcnt lgkmcnt(4)
	v_mfma_f32_32x32x16_bf16 v[82:97], v[172:175], v[120:123], v[82:97]
	s_waitcnt lgkmcnt(3)
	v_mfma_f32_32x32x16_bf16 v[98:113], v[176:179], v[124:127], v[98:113]
	s_waitcnt lgkmcnt(2)
	v_mfma_f32_32x32x16_bf16 v[82:97], v[240:243], v[124:127], v[82:97]
	s_waitcnt lgkmcnt(1)
	v_mfma_f32_32x32x16_bf16 v[98:113], v[148:151], v[128:131], v[98:113]
	s_waitcnt lgkmcnt(0)
	v_mfma_f32_32x32x16_bf16 v[82:97], v[152:155], v[128:131], v[82:97]
	s_nop 7
	s_nop 3
	v_exp_f32_e32 v148, v98
	v_exp_f32_e32 v164, v82
	v_exp_f32_e32 v149, v99
	v_exp_f32_e32 v165, v83
	v_add_f32_e32 v237, 0, v148
	v_add_f32_e32 v238, 0, v164
	v_exp_f32_e32 v150, v100
	v_exp_f32_e32 v166, v84
	v_add_f32_e32 v237, v149, v237
	v_add_f32_e32 v238, v165, v238
	v_exp_f32_e32 v151, v101
	v_exp_f32_e32 v167, v85
	v_add_f32_e32 v237, v150, v237
	v_add_f32_e32 v238, v166, v238
	v_exp_f32_e32 v152, v102
	v_exp_f32_e32 v168, v86
	v_add_f32_e32 v237, v151, v237
	v_add_f32_e32 v238, v167, v238
	v_exp_f32_e32 v153, v103
	v_exp_f32_e32 v169, v87
	v_add_f32_e32 v237, v152, v237
	v_add_f32_e32 v238, v168, v238
	v_exp_f32_e32 v154, v104
	v_exp_f32_e32 v170, v88
	v_add_f32_e32 v237, v153, v237
	v_add_f32_e32 v238, v169, v238
	v_exp_f32_e32 v155, v105
	v_exp_f32_e32 v171, v89
	v_add_f32_e32 v237, v154, v237
	v_add_f32_e32 v238, v170, v238
	v_exp_f32_e32 v156, v106
	v_exp_f32_e32 v172, v90
	v_add_f32_e32 v237, v155, v237
	v_add_f32_e32 v238, v171, v238
	v_exp_f32_e32 v157, v107
	v_exp_f32_e32 v173, v91
	v_add_f32_e32 v237, v156, v237
	v_add_f32_e32 v238, v172, v238
	v_exp_f32_e32 v158, v108
	v_exp_f32_e32 v174, v92
	v_add_f32_e32 v237, v157, v237
	v_add_f32_e32 v238, v173, v238
	v_exp_f32_e32 v159, v109
	v_exp_f32_e32 v175, v93
	v_add_f32_e32 v237, v158, v237
	v_add_f32_e32 v238, v174, v238
	v_exp_f32_e32 v160, v110
	v_exp_f32_e32 v176, v94
	v_add_f32_e32 v237, v159, v237
	v_add_f32_e32 v238, v175, v238
	v_exp_f32_e32 v161, v111
	v_exp_f32_e32 v177, v95
	v_add_f32_e32 v237, v160, v237
	v_add_f32_e32 v238, v176, v238
	v_exp_f32_e32 v162, v112
	v_exp_f32_e32 v178, v96
	v_add_f32_e32 v237, v161, v237
	v_add_f32_e32 v238, v177, v238
	v_exp_f32_e32 v163, v113
	v_exp_f32_e32 v179, v97
	v_add_f32_e32 v237, v162, v237
	v_add_f32_e32 v238, v178, v238
	s_nop 0
	v_add_f32_e32 v237, v163, v237
	v_add_f32_e32 v238, v179, v238
	v_add_f32_e32 v204, v237, v238
	v_cmp_lt_f32_e32 vcc, s85, v204
	s_cbranch_vccnz .Lda_s_slow
; __device__ __forceinline__ unsigned cvtpk(float lo, float hi) { f32x2 v = {lo, hi}; bf16x2_t b = __builtin_convertvector(v, bf16x2_t); return __builtin_bit_cast(unsigned, b); }
; template <bool DIFF>
; __device__ __forceinline__ void attn_unit(const AttnP& A, int b, int h, int qi, ldsp lds) {
;     ...
;             bf16x8 pw[4];
; #pragma unroll
;             for (int j = 0; j < 4; ++j) {
;                 u32x4 pk;
;                 if (j < 2) { const int rb = 8 * (j & 1); pk.x = cvtpk(s0[rb], s0[rb + 1]); pk.y = cvtpk(s0[rb + 2], s0[rb + 3]); pk.z = cvtpk(s0[rb + 4], s0[rb + 5]); pk.w = cvtpk(s0[rb + 6], s0[rb + 7]); }
;                 else { const int rb = 8 * (j & 1); pk.x = cvtpk(s1[rb], s1[rb + 1]); pk.y = cvtpk(s1[rb + 2], s1[rb + 3]); pk.z = cvtpk(s1[rb + 4], s1[rb + 5]); pk.w = cvtpk(s1[rb + 6], s1[rb + 7]); }
;                 pw[j] = __builtin_bit_cast(bf16x8, pk);
;             }
;             __builtin_amdgcn_sched_barrier(0);
;             __builtin_amdgcn_s_setprio(1);
; #pragma unroll
;             for (int t = 0; t < 2; ++t)
; #pragma unroll
;                 for (int j = 0; j < 4; ++j) {
;                     const bf16x8 vf = (bf16x8){vlo[t * 4 + j][0], vlo[t * 4 + j][1], vlo[t * 4 + j][2], vlo[t * 4 + j][3], vhi[t * 4 + j][0], vhi[t * 4 + j][1], vhi[t * 4 + j][2], vhi[t * 4 + j][3]};
;                     o[t] = __builtin_amdgcn_mfma_f32_32x32x16_bf16(vf, pw[j], o[t], 0, 0, 0);
;                 }
;             if (DIFF) {
; #pragma unroll
;                 for (int t = 2; t < NTD; ++t)
; #pragma unroll
;                     for (int j = 0; j < 4; ++j) { vlo[(t - 2) * 4 + j] = vtr(Vb + trb + (16 * j) * VP + t * 64); vhi[(t - 2) * 4 + j] = vtr(Vb + trb + (16 * j + 8) * VP + t * 64); }
;                 __builtin_amdgcn_sched_barrier(0);
; #pragma unroll
;                 for (int t = 2; t < NTD; ++t)
; #pragma unroll
;                     for (int j = 0; j < 4; ++j) {
;                         const int i = (t - 2) * 4 + j;
;                         const bf16x8 vf = (bf16x8){vlo[i][0], vlo[i][1], vlo[i][2], vlo[i][3], vhi[i][0], vhi[i][1], vhi[i][2], vhi[i][3]};
;                         o[t] = __builtin_amdgcn_mfma_f32_32x32x16_bf16(vf, pw[j], o[t], 0, 0, 0);
;                     }
;             }
;             __builtin_amdgcn_s_setprio(0);
;         }
;         if (kt + 1 < nt) STORE_TILE((kt + 1) & 1);
;         __syncthreads();
;     }
	v_cvt_pk_bf16_f32 v98, v148, v149
	v_cvt_pk_bf16_f32 v99, v150, v151
	v_cvt_pk_bf16_f32 v100, v152, v153
	v_cvt_pk_bf16_f32 v101, v154, v155
	v_cvt_pk_bf16_f32 v102, v156, v157
	v_cvt_pk_bf16_f32 v103, v158, v159
	v_cvt_pk_bf16_f32 v104, v160, v161
	v_cvt_pk_bf16_f32 v105, v162, v163
	v_cvt_pk_bf16_f32 v82, v164, v165
	v_cvt_pk_bf16_f32 v83, v166, v167
	v_cvt_pk_bf16_f32 v84, v168, v169
	v_cvt_pk_bf16_f32 v85, v170, v171
	v_cvt_pk_bf16_f32 v86, v172, v173
	v_cvt_pk_bf16_f32 v87, v174, v175
	v_cvt_pk_bf16_f32 v88, v176, v177
	v_cvt_pk_bf16_f32 v89, v178, v179
	v_add_f32_e32 v230, v204, v230
	s_waitcnt lgkmcnt(0)
	s_barrier
	s_add_i32 s75, s75, 1
	s_add_i32 s74, s74, 64
	s_cmp_gt_i32 s75, s23
	s_cbranch_scc1 .Lda_gen
.Lda_s_odd:
	ds_read_b64_tr_b16 v[148:149], v231 offset:17472
	ds_read_b64_tr_b16 v[150:151], v231 offset:20032
	ds_read_b64_tr_b16 v[152:153], v231 offset:17408
	ds_read_b64_tr_b16 v[154:155], v231 offset:19968
	ds_read_b64_tr_b16 v[156:157], v231 offset:22592
	ds_read_b64_tr_b16 v[158:159], v231 offset:25152
	ds_read_b64_tr_b16 v[160:161], v231 offset:22528
	ds_read_b64_tr_b16 v[162:163], v231 offset:25088
	ds_read_b64_tr_b16 v[164:165], v231 offset:27712
	ds_read_b64_tr_b16 v[166:167], v231 offset:30272
	ds_read_b64_tr_b16 v[168:169], v231 offset:27648
	ds_read_b64_tr_b16 v[170:171], v231 offset:30208
	ds_read_b64_tr_b16 v[172:173], v231 offset:32768
	ds_read_b64_tr_b16 v[174:175], v231 offset:35328
	ds_read_b64_tr_b16 v[176:177], v231 offset:32832
	ds_read_b64_tr_b16 v[178:179], v231 offset:35392
	s_waitcnt lgkmcnt(14)
	v_mfma_f32_32x32x16_bf16 v[34:49], v[148:151], v[98:101], v[34:49]
	ds_read_b64_tr_b16 v[90:91], v231 offset:17536
	ds_read_b64_tr_b16 v[92:93], v231 offset:20096
	s_waitcnt lgkmcnt(14)
	v_mfma_f32_32x32x16_bf16 v[50:65], v[152:155], v[98:101], v[50:65]
	ds_read_b64_tr_b16 v[94:95], v231 offset:17600
	ds_read_b64_tr_b16 v[96:97], v231 offset:20160
	s_waitcnt lgkmcnt(14)
	v_mfma_f32_32x32x16_bf16 v[34:49], v[156:159], v[102:105], v[34:49]
	ds_read_b64_tr_b16 v[106:107], v231 offset:22656
	ds_read_b64_tr_b16 v[108:109], v231 offset:25216
	s_waitcnt lgkmcnt(14)
	v_mfma_f32_32x32x16_bf16 v[50:65], v[160:163], v[102:105], v[50:65]
	ds_read_b64_tr_b16 v[110:111], v231 offset:22720
	ds_read_b64_tr_b16 v[112:113], v231 offset:25280
	s_waitcnt lgkmcnt(14)
	v_mfma_f32_32x32x16_bf16 v[34:49], v[164:167], v[82:85], v[34:49]
	ds_read_b64_tr_b16 v[240:241], v231 offset:27776
	ds_read_b64_tr_b16 v[242:243], v231 offset:30336
	s_waitcnt lgkmcnt(14)
	v_mfma_f32_32x32x16_bf16 v[50:65], v[168:171], v[82:85], v[50:65]
	ds_read_b64_tr_b16 v[148:149], v231 offset:27840
	ds_read_b64_tr_b16 v[150:151], v231 offset:30400
	s_waitcnt lgkmcnt(14)
	v_mfma_f32_32x32x16_bf16 v[50:65], v[172:175], v[86:89], v[50:65]
	ds_read_b64_tr_b16 v[152:153], v231 offset:32896
	ds_read_b64_tr_b16 v[154:155], v231 offset:35456
	s_waitcnt lgkmcnt(14)
	v_mfma_f32_32x32x16_bf16 v[34:49], v[176:179], v[86:89], v[34:49]
	ds_read_b64_tr_b16 v[156:157], v231 offset:32960
	ds_read_b64_tr_b16 v[158:159], v231 offset:35520
	s_waitcnt vmcnt(0)
	ds_write_b128 v226, v[132:135]
	ds_write_b128 v228, v[140:143]
	ds_write_b128 v227, v[136:139] offset:55552
	ds_write_b128 v229, v[144:147] offset:55552
	global_load_dwordx4 v[136:139], v[196:197], off offset:2048
	global_load_dwordx4 v[144:147], v[198:199], off offset:2048
	v_lshl_add_u64 v[196:197], v[196:197], 0, s[26:27]
	v_lshl_add_u64 v[198:199], v[198:199], 0, s[26:27]
	global_load_dwordx4 v[132:135], v[196:197], off offset:1024
	global_load_dwordx4 v[140:143], v[198:199], off offset:1024
	s_waitcnt lgkmcnt(15)
	v_mfma_f32_32x32x16_bf16 v[18:33], v[90:93], v[98:101], v[18:33]
	ds_read_b128 v[160:163], v234 offset:38144
	s_waitcnt lgkmcnt(15)
	v_mfma_f32_32x32x16_bf16 v[2:17], v[94:97], v[98:101], v[2:17]
	ds_read_b128 v[164:167], v234 offset:46848
	s_waitcnt lgkmcnt(15)
	v_mfma_f32_32x32x16_bf16 v[18:33], v[106:109], v[102:105], v[18:33]
	ds_read_b128 v[168:171], v234 offset:38176
	s_waitcnt lgkmcnt(15)
; __device__ __forceinline__ unsigned cvtpk(float lo, float hi) { f32x2 v = {lo, hi}; bf16x2_t b = __builtin_convertvector(v, bf16x2_t); return __builtin_bit_cast(unsigned, b); }
; __device__ __forceinline__ s16x4 vtr(ldsp p) { return __builtin_bit_cast(s16x4, __builtin_amdgcn_ds_read_tr16_b64_v4i16((LAS v4i16_t*)p)); }
; #define MASK_BLOCK() do { if (kt == 0 || kt >= diag0) { \
;             _Pragma("unroll") for (int r = 0; r < 16; ++r) { const int kpp = 64 * kt + crow(r, hi); \
;                 if (kpp < 48 || kpp > q_pp) s0[r] = -INFINITY; \
;                 if (kpp + 32 < 48 || kpp + 32 > q_pp) s1[r] = -INFINITY; } } } while (0)
; #define EXPSUM_BLOCK() do { psa = 0.f; psb = 0.f; \
;             _Pragma("unroll") for (int r = 0; r < 16; ++r) { s0[r] = __builtin_amdgcn_exp2f(s0[r]); s1[r] = __builtin_amdgcn_exp2f(s1[r]); psa += s0[r]; asm("" : "+v"(psa)); psb += s1[r]; asm("" : "+v"(psb)); } } while (0)
; template <bool DIFF>
; __device__ __forceinline__ void attn_unit(const AttnP& A, int b, int h, int qi, ldsp lds) {
;     ...
;             QK_BLOCK();
;             s16x4 vlo[8], vhi[8];
; #pragma unroll
;             for (int t = 0; t < 2; ++t)
; #pragma unroll
;                 for (int j = 0; j < 4; ++j) { vlo[t * 4 + j] = vtr(Vb + trb + (16 * j) * VP + t * 64); vhi[t * 4 + j] = vtr(Vb + trb + (16 * j + 8) * VP + t * 64); }
;             __builtin_amdgcn_sched_barrier(0);
;             MASK_BLOCK();
;             bool full = (kt == kt0);
;             float psa, psb;
;             if (!full) {
;                 EXPSUM_BLOCK();
;                 if (__any(psa + psb > 1.0e18f)) { full = true; QK_BLOCK();
;     ...
;             bf16x8 pw[4];
; #pragma unroll
;             for (int j = 0; j < 4; ++j) {
;                 u32x4 pk;
;                 if (j < 2) { const int rb = 8 * (j & 1); pk.x = cvtpk(s0[rb], s0[rb + 1]); pk.y = cvtpk(s0[rb + 2], s0[rb + 3]); pk.z = cvtpk(s0[rb + 4], s0[rb + 5]); pk.w = cvtpk(s0[rb + 6], s0[rb + 7]); }
;                 else { const int rb = 8 * (j & 1); pk.x = cvtpk(s1[rb], s1[rb + 1]); pk.y = cvtpk(s1[rb + 2], s1[rb + 3]); pk.z = cvtpk(s1[rb + 4], s1[rb + 5]); pk.w = cvtpk(s1[rb + 6], s1[rb + 7]); }
;                 pw[j] = __builtin_bit_cast(bf16x8, pk);
;             }
	v_mfma_f32_32x32x16_bf16 v[2:17], v[110:113], v[102:105], v[2:17]
	ds_read_b128 v[172:175], v234 offset:46880
	s_waitcnt lgkmcnt(14)
	v_mfma_f32_32x32x16_bf16 v[18:33], v[240:243], v[82:85], v[18:33]
	ds_read_b128 v[176:179], v234 offset:38208
	s_waitcnt lgkmcnt(13)
	v_mfma_f32_32x32x16_bf16 v[2:17], v[148:151], v[82:85], v[2:17]
	ds_read_b128 v[240:243], v234 offset:46912
	s_waitcnt lgkmcnt(12)
	v_mfma_f32_32x32x16_bf16 v[18:33], v[152:155], v[86:89], v[18:33]
	ds_read_b128 v[148:151], v234 offset:38240
	s_waitcnt lgkmcnt(11)
	v_mfma_f32_32x32x16_bf16 v[2:17], v[156:159], v[86:89], v[2:17]
	ds_read_b128 v[152:155], v234 offset:46944
	s_waitcnt lgkmcnt(7)
	v_mfma_f32_32x32x16_bf16 v[98:113], v[160:163], v[116:119], v[66:81]
	s_waitcnt lgkmcnt(6)
	v_mfma_f32_32x32x16_bf16 v[82:97], v[164:167], v[116:119], v[66:81]
	s_waitcnt lgkmcnt(5)
	v_mfma_f32_32x32x16_bf16 v[98:113], v[168:171], v[120:123], v[98:113]
	s_waitcnt lgkmcnt(4)
	v_mfma_f32_32x32x16_bf16 v[82:97], v[172:175], v[120:123], v[82:97]
	s_waitcnt lgkmcnt(3)
	v_mfma_f32_32x32x16_bf16 v[98:113], v[176:179], v[124:127], v[98:113]
	s_waitcnt lgkmcnt(2)
	v_mfma_f32_32x32x16_bf16 v[82:97], v[240:243], v[124:127], v[82:97]
	s_waitcnt lgkmcnt(1)
	v_mfma_f32_32x32x16_bf16 v[98:113], v[148:151], v[128:131], v[98:113]
	s_waitcnt lgkmcnt(0)
	v_mfma_f32_32x32x16_bf16 v[82:97], v[152:155], v[128:131], v[82:97]
	s_nop 7
	s_nop 3
	v_exp_f32_e32 v148, v98
	v_exp_f32_e32 v164, v82
	v_exp_f32_e32 v149, v99
	v_exp_f32_e32 v165, v83
	v_add_f32_e32 v237, 0, v148
	v_add_f32_e32 v238, 0, v164
	v_exp_f32_e32 v150, v100
	v_exp_f32_e32 v166, v84
	v_add_f32_e32 v237, v149, v237
	v_add_f32_e32 v238, v165, v238
	v_exp_f32_e32 v151, v101
	v_exp_f32_e32 v167, v85
	v_add_f32_e32 v237, v150, v237
	v_add_f32_e32 v238, v166, v238
	v_exp_f32_e32 v152, v102
	v_exp_f32_e32 v168, v86
	v_add_f32_e32 v237, v151, v237
	v_add_f32_e32 v238, v167, v238
	v_exp_f32_e32 v153, v103
	v_exp_f32_e32 v169, v87
	v_add_f32_e32 v237, v152, v237
	v_add_f32_e32 v238, v168, v238
	v_exp_f32_e32 v154, v104
	v_exp_f32_e32 v170, v88
	v_add_f32_e32 v237, v153, v237
	v_add_f32_e32 v238, v169, v238
	v_exp_f32_e32 v155, v105
	v_exp_f32_e32 v171, v89
	v_add_f32_e32 v237, v154, v237
	v_add_f32_e32 v238, v170, v238
	v_exp_f32_e32 v156, v106
	v_exp_f32_e32 v172, v90
	v_add_f32_e32 v237, v155, v237
	v_add_f32_e32 v238, v171, v238
	v_exp_f32_e32 v157, v107
	v_exp_f32_e32 v173, v91
	v_add_f32_e32 v237, v156, v237
	v_add_f32_e32 v238, v172, v238
	v_exp_f32_e32 v158, v108
	v_exp_f32_e32 v174, v92
	v_add_f32_e32 v237, v157, v237
	v_add_f32_e32 v238, v173, v238
	v_exp_f32_e32 v159, v109
	v_exp_f32_e32 v175, v93
	v_add_f32_e32 v237, v158, v237
	v_add_f32_e32 v238, v174, v238
	v_exp_f32_e32 v160, v110
	v_exp_f32_e32 v176, v94
	v_add_f32_e32 v237, v159, v237
	v_add_f32_e32 v238, v175, v238
	v_exp_f32_e32 v161, v111
	v_exp_f32_e32 v177, v95
	v_add_f32_e32 v237, v160, v237
	v_add_f32_e32 v238, v176, v238
	v_exp_f32_e32 v162, v112
	v_exp_f32_e32 v178, v96
	v_add_f32_e32 v237, v161, v237
	v_add_f32_e32 v238, v177, v238
	v_exp_f32_e32 v163, v113
	v_exp_f32_e32 v179, v97
	v_add_f32_e32 v237, v162, v237
	v_add_f32_e32 v238, v178, v238
	s_nop 0
	v_add_f32_e32 v237, v163, v237
	v_add_f32_e32 v238, v179, v238
	v_add_f32_e32 v204, v237, v238
	v_cmp_lt_f32_e32 vcc, s85, v204
	s_cbranch_vccnz .Lda_s_slow
	v_cvt_pk_bf16_f32 v98, v148, v149
	v_cvt_pk_bf16_f32 v99, v150, v151
	v_cvt_pk_bf16_f32 v100, v152, v153
	v_cvt_pk_bf16_f32 v101, v154, v155
	v_cvt_pk_bf16_f32 v102, v156, v157
	v_cvt_pk_bf16_f32 v103, v158, v159
	v_cvt_pk_bf16_f32 v104, v160, v161
	v_cvt_pk_bf16_f32 v105, v162, v163
	v_cvt_pk_bf16_f32 v82, v164, v165
	v_cvt_pk_bf16_f32 v83, v166, v167
	v_cvt_pk_bf16_f32 v84, v168, v169
	v_cvt_pk_bf16_f32 v85, v170, v171
	v_cvt_pk_bf16_f32 v86, v172, v173
	v_cvt_pk_bf16_f32 v87, v174, v175
	v_cvt_pk_bf16_f32 v88, v176, v177
	v_cvt_pk_bf16_f32 v89, v178, v179
	v_add_f32_e32 v230, v204, v230
	s_waitcnt lgkmcnt(0)
	s_barrier
	s_add_i32 s75, s75, 1
	s_add_i32 s74, s74, 64
	s_cmp_le_i32 s75, s23
	s_cbranch_scc1 .Lda_s_even
